# attention items re-decoded so each XCD works on all query blocks of one (batch, kv head) at a time: neighbours' K/V rows found in the XCD's L2
# speedup vs baseline: 1.0024x; 1.0024x over previous
.LBB0_394:
	s_andn2_b64 vcc, exec, s[0:1]
	s_mov_b32 s21, 32
	s_cbranch_vccnz .LBB0_396
	s_bfe_u32 s21, s80, 0x50003
	s_lshr_b32 s20, s80, 8
	s_lshl_b32 s20, s20, 1
	s_bfe_u32 s22, s80, 0x10002
	s_or_b32 s20, s20, s22
